# LN phase: previous row's stores no longer drained at the row-loop head nor before the second statistics pass (layers >= 1)
# speedup vs baseline: 1.0188x; 1.0072x over previous
; #define BIDX bid_()
; __device__ __forceinline__ void row_stats(const f32x4 (&v)[8], float& mean, float& rstd) {
;     float s = 0.f;
; #pragma unroll
;     for (int i = 0; i < 8; ++i) s += v[i][0] + v[i][1] + v[i][2] + v[i][3];
;     mean = wsum(s) * (1.f / 2048.f);
;     float q = 0.f;
; #pragma unroll
;     for (int i = 0; i < 8; ++i) { const f32x4 d = v[i] - mean; q += d[0] * d[0] + d[1] * d[1] + d[2] * d[2] + d[3] * d[3]; }
;     rstd = rsqrtf(wsum(q) * (1.f / 2048.f) + LN_EPS);
; __device__ void phase_ln(const Params& p, int l) {
;     ...
;     for (int row = BIDX * 8 + wid; row < MROWS; row += nw) {
;         const bool isctx = row < CTXROWS;
;         if (fin && isctx) continue;
;         const int b = isctx ? (row >> 8) : ((row - CTXROWS) >> 13);
;         float* rw = isctx ? p.RC + (size_t)row * D : p.out + (size_t)(row - CTXROWS) * D;
;         const float* src = (l == 0) ? (isctx ? p.ctx + (size_t)row * D : p.x + (size_t)(row - CTXROWS) * D) : rw;
;         f32x4 v[8];
; #pragma unroll
;         for (int i = 0; i < 8; ++i) v[i] = *(const f32x4*)(src + i * 256 + lane * 4);
;         float mean, rstd;
;         if (l > 0) {
;             row_stats(v, mean, rstd);
.LBB0_345:
	s_movk_i32 s6, 0x1ff
	v_cmp_lt_i32_e64 s[8:9], s6, v32
	s_movk_i32 s6, 0x200
	v_cmp_gt_i32_e64 s[6:7], s6, v32
	s_and_b64 s[38:39], s[20:21], s[6:7]
	s_xor_b64 s[42:43], s[38:39], -1
	s_and_saveexec_b64 s[38:39], s[42:43]
	s_cbranch_execz .LBB0_344
	v_add_u32_e32 v60, 0xfffffe00, v32
	v_mov_b32_e32 v2, s13
	v_mov_b32_e32 v3, s37
	v_cndmask_b32_e64 v1, 0, v33, s[6:7]
	v_cndmask_b32_e64 v0, v60, v32, s[6:7]
	v_cndmask_b32_e64 v3, v2, v3, s[6:7]
	v_mov_b32_e32 v2, s12
	v_mov_b32_e32 v4, s3
	v_cndmask_b32_e64 v2, v2, v4, s[6:7]
	v_lshlrev_b64 v[0:1], 13, v[0:1]
	v_lshl_add_u64 v[62:63], v[2:3], 0, v[0:1]
	s_andn2_b64 vcc, exec, s[24:25]
	v_mov_b64_e32 v[0:1], v[62:63]
	s_cbranch_vccnz .LBB0_350
	v_mov_b32_e32 v61, v149
	v_mov_b64_e32 v[0:1], v[58:59]
	s_and_saveexec_b64 s[42:43], s[8:9]
	v_lshlrev_b64 v[0:1], 13, v[60:61]
	v_lshl_add_u64 v[0:1], s[10:11], 0, v[0:1]
	s_or_b64 exec, exec, s[42:43]
.LBB0_350:
	v_lshlrev_b32_e32 v148, 2, v34
	v_lshl_add_u64 v[0:1], v[0:1], 0, v[148:149]
	global_load_dwordx4 v[28:31], v[0:1], off
	global_load_dwordx4 v[24:27], v[0:1], off offset:1024
	global_load_dwordx4 v[20:23], v[0:1], off offset:2048
	global_load_dwordx4 v[16:19], v[0:1], off offset:3072
	v_add_co_u32_e32 v0, vcc, 0x1000, v0
	s_nop 1
	v_addc_co_u32_e32 v1, vcc, 0, v1, vcc
	global_load_dwordx4 v[12:15], v[0:1], off
	global_load_dwordx4 v[8:11], v[0:1], off offset:1024
	global_load_dwordx4 v[4:7], v[0:1], off offset:2048
	s_nop 0
	global_load_dwordx4 v[0:3], v[0:1], off offset:3072
	s_andn2_b64 vcc, exec, s[26:27]
	s_cbranch_vccnz .LBB0_352
	s_waitcnt vmcnt(0)
	v_add_f32_e32 v35, v28, v29
	v_add_f32_e32 v35, v30, v35
	v_add_f32_e32 v61, v24, v25
	v_add_f32_e32 v35, v31, v35
	v_add_f32_e32 v61, v26, v61
	v_add_f32_e32 v35, 0, v35
	v_add_f32_e32 v61, v27, v61
	v_add_f32_e32 v35, v35, v61
	v_add_f32_e32 v61, v20, v21
	v_add_f32_e32 v61, v22, v61
	v_add_f32_e32 v61, v23, v61
	v_add_f32_e32 v35, v35, v61
	v_add_f32_e32 v61, v16, v17
	v_mov_b32_e32 v64, v12
	v_mov_b32_e32 v65, v8
	v_mov_b32_e32 v66, v13
	v_mov_b32_e32 v67, v9
	v_add_f32_e32 v61, v18, v61
	v_pk_add_f32 v[64:65], v[64:65], v[66:67]
	v_mov_b32_e32 v66, v14
	v_mov_b32_e32 v67, v10
	v_add_f32_e32 v61, v19, v61
	v_pk_add_f32 v[64:65], v[66:67], v[64:65]
	v_mov_b32_e32 v66, v15
	v_mov_b32_e32 v67, v11
	v_add_f32_e32 v35, v35, v61
	v_pk_add_f32 v[64:65], v[66:67], v[64:65]
	v_mov_b32_e32 v66, v5
	v_add_f32_e32 v35, v35, v64
	v_add_f32_e32 v35, v35, v65
	v_mov_b32_e32 v64, v4
	v_mov_b32_e32 v65, v0
	v_mov_b32_e32 v67, v1
	v_pk_add_f32 v[64:65], v[64:65], v[66:67]
	v_mov_b32_e32 v66, v6
	v_mov_b32_e32 v67, v2
	v_pk_add_f32 v[64:65], v[66:67], v[64:65]
	v_mov_b32_e32 v66, v7
	v_mov_b32_e32 v67, v3
	v_pk_add_f32 v[64:65], v[66:67], v[64:65]
	v_cmp_lt_i32_e32 vcc, v211, v210
	v_add_f32_e32 v35, v35, v64
	v_add_f32_e32 v35, v35, v65
	v_cndmask_b32_e32 v61, v208, v211, vcc
	v_lshlrev_b32_e32 v61, 2, v61
	ds_bpermute_b32 v64, v61, v35
	v_cmp_lt_i32_e32 vcc, v212, v210
	v_lshl_add_u64 v[74:75], v[62:63], 0, v[148:149]
	s_waitcnt lgkmcnt(0)
	v_add_f32_e32 v35, v35, v64
	v_cndmask_b32_e32 v64, v208, v212, vcc
	v_lshlrev_b32_e32 v68, 2, v64
	ds_bpermute_b32 v64, v68, v35
	v_cmp_lt_i32_e32 vcc, v213, v210
	s_waitcnt lgkmcnt(0)
	v_add_f32_e32 v35, v35, v64
	v_cndmask_b32_e32 v64, v208, v213, vcc
	v_lshlrev_b32_e32 v69, 2, v64
	ds_bpermute_b32 v64, v69, v35
	v_cmp_lt_i32_e32 vcc, v214, v210
	s_waitcnt lgkmcnt(0)
	v_add_f32_e32 v35, v35, v64
	v_cndmask_b32_e32 v64, v208, v214, vcc
	v_lshlrev_b32_e32 v70, 2, v64
	ds_bpermute_b32 v64, v70, v35
	v_cmp_lt_i32_e32 vcc, v215, v210
	s_waitcnt lgkmcnt(0)
	v_add_f32_e32 v35, v35, v64
	v_cndmask_b32_e32 v64, v208, v215, vcc
	v_lshlrev_b32_e32 v71, 2, v64
	ds_bpermute_b32 v64, v71, v35
	v_cmp_lt_i32_e32 vcc, v216, v210
	s_waitcnt lgkmcnt(0)
	v_add_f32_e32 v35, v35, v64
	v_cndmask_b32_e32 v64, v208, v216, vcc
	v_lshlrev_b32_e32 v72, 2, v64
	ds_bpermute_b32 v64, v72, v35
	s_waitcnt lgkmcnt(0)
	v_add_f32_e32 v35, v35, v64
	v_fmac_f32_e32 v29, 0xba000000, v35
	v_fmac_f32_e32 v25, 0xba000000, v35
	v_fmamk_f32 v28, v35, 0xba000000, v28
	v_mul_f32_e32 v64, v29, v29
	v_fmamk_f32 v24, v35, 0xba000000, v24
	v_mul_f32_e32 v65, v25, v25
	v_fmamk_f32 v30, v35, 0xba000000, v30
	v_fmac_f32_e32 v64, v28, v28
	v_fmamk_f32 v26, v35, 0xba000000, v26
	v_fmac_f32_e32 v65, v24, v24
	v_fmamk_f32 v31, v35, 0xba000000, v31
	v_fmac_f32_e32 v64, v30, v30
	v_fmamk_f32 v27, v35, 0xba000000, v27
	v_fmac_f32_e32 v65, v26, v26
	v_fmac_f32_e32 v64, v31, v31
	v_fmac_f32_e32 v65, v27, v27
	v_fmac_f32_e32 v21, 0xba000000, v35
	v_add_f32_e32 v64, v64, v65
	v_fmamk_f32 v20, v35, 0xba000000, v20
	v_mul_f32_e32 v65, v21, v21
	v_fmamk_f32 v22, v35, 0xba000000, v22
	v_fmac_f32_e32 v65, v20, v20
	v_fmamk_f32 v23, v35, 0xba000000, v23
	v_fmac_f32_e32 v65, v22, v22
	v_fmac_f32_e32 v65, v23, v23
	v_fmac_f32_e32 v17, 0xba000000, v35
	v_add_f32_e32 v64, v65, v64
	v_fmamk_f32 v16, v35, 0xba000000, v16
	v_mul_f32_e32 v65, v17, v17
	v_fmamk_f32 v18, v35, 0xba000000, v18
	v_fmac_f32_e32 v65, v16, v16
	v_fmamk_f32 v19, v35, 0xba000000, v19
	v_fmac_f32_e32 v65, v18, v18
	v_fmamk_f32 v13, v35, 0xba000000, v13
	v_fmamk_f32 v9, v35, 0xba000000, v9
	v_fmac_f32_e32 v65, v19, v19
	v_fmac_f32_e32 v12, 0xba000000, v35
	v_fmac_f32_e32 v8, 0xba000000, v35
	v_mov_b32_e32 v66, v9
	v_mov_b32_e32 v67, v13
	v_add_f32_e32 v73, v65, v64
	v_fmamk_f32 v14, v35, 0xba000000, v14
	v_fmamk_f32 v10, v35, 0xba000000, v10
	v_mov_b32_e32 v64, v8
	v_mov_b32_e32 v65, v12
	v_pk_mul_f32 v[66:67], v[66:67], v[66:67]
	v_fmamk_f32 v15, v35, 0xba000000, v15
	v_fmamk_f32 v11, v35, 0xba000000, v11
	v_pk_fma_f32 v[64:65], v[64:65], v[64:65], v[66:67]
	v_mov_b32_e32 v66, v10
	v_mov_b32_e32 v67, v14
	v_pk_fma_f32 v[64:65], v[66:67], v[66:67], v[64:65]
	v_mov_b32_e32 v66, v11
	v_mov_b32_e32 v67, v15
	v_pk_fma_f32 v[64:65], v[66:67], v[66:67], v[64:65]
	v_fmamk_f32 v5, v35, 0xba000000, v5
	v_fmamk_f32 v1, v35, 0xba000000, v1
	v_add_f32_e32 v65, v65, v73
	v_fmac_f32_e32 v4, 0xba000000, v35
	v_fmac_f32_e32 v0, 0xba000000, v35
	v_mov_b32_e32 v66, v1
	v_mov_b32_e32 v67, v5
	v_add_f32_e32 v73, v64, v65
	v_fmamk_f32 v6, v35, 0xba000000, v6
	v_mov_b32_e32 v64, v0
	v_mov_b32_e32 v65, v4
	v_pk_mul_f32 v[66:67], v[66:67], v[66:67]
	v_fmamk_f32 v2, v35, 0xba000000, v2
	v_pk_fma_f32 v[64:65], v[64:65], v[64:65], v[66:67]
	v_mov_b32_e32 v66, v2
	v_mov_b32_e32 v67, v6
	v_fmamk_f32 v7, v35, 0xba000000, v7
	v_fmamk_f32 v3, v35, 0xba000000, v3
	v_pk_fma_f32 v[64:65], v[66:67], v[66:67], v[64:65]
	v_mov_b32_e32 v66, v3
	v_mov_b32_e32 v67, v7
	v_pk_fma_f32 v[64:65], v[66:67], v[66:67], v[64:65]
	s_nop 0
	v_add_f32_e32 v35, v65, v73
	v_add_f32_e32 v35, v64, v35
	ds_bpermute_b32 v61, v61, v35
	s_waitcnt lgkmcnt(0)
; __device__ __forceinline__ void row_stats(const f32x4 (&v)[8], float& mean, float& rstd) {
;     ...
;     mean = wsum(s) * (1.f / 2048.f);
;     float q = 0.f;
; #pragma unroll
;     for (int i = 0; i < 8; ++i) { const f32x4 d = v[i] - mean; q += d[0] * d[0] + d[1] * d[1] + d[2] * d[2] + d[3] * d[3]; }
;     rstd = rsqrtf(wsum(q) * (1.f / 2048.f) + LN_EPS);
; __device__ void phase_ln(const Params& p, int l) {
;     ...
;             const float* g = p.ln_g + (size_t)(l - 1) * D; const float* bb = p.ln_b + (size_t)(l - 1) * D;
; #pragma unroll
;             for (int i = 0; i < 8; ++i) { const f32x4 gv = *(const f32x4*)(g + i * 256 + lane * 4), bv = *(const f32x4*)(bb + i * 256 + lane * 4);
;                 v[i] = (v[i] - mean) * rstd * gv + bv; *(f32x4*)(rw + i * 256 + lane * 4) = v[i]; }
;         }
;         if (fin) continue;
	v_add_f32_e32 v35, v35, v61
	ds_bpermute_b32 v61, v68, v35
	s_waitcnt lgkmcnt(0)
	v_add_f32_e32 v35, v35, v61
	ds_bpermute_b32 v61, v69, v35
	s_waitcnt lgkmcnt(0)
	v_add_f32_e32 v35, v35, v61
	ds_bpermute_b32 v61, v70, v35
	s_waitcnt lgkmcnt(0)
	v_add_f32_e32 v35, v35, v61
	ds_bpermute_b32 v61, v71, v35
	v_mov_b64_e32 v[64:65], v[88:89]
	v_mov_b64_e32 v[66:67], v[90:91]
	v_mov_b64_e32 v[68:69], v[120:121]
	v_mov_b64_e32 v[70:71], v[122:123]
	s_waitcnt lgkmcnt(0)
	v_add_f32_e32 v35, v35, v61
	ds_bpermute_b32 v61, v72, v35
	s_waitcnt lgkmcnt(0)
	v_add_f32_e32 v35, v35, v61
	v_fmamk_f32 v35, v35, 0x3a000000, v207
	v_mul_f32_e32 v61, 0x4b800000, v35
	v_cmp_gt_f32_e32 vcc, s41, v35
	s_nop 1
	v_cndmask_b32_e32 v35, v35, v61, vcc
	v_rsq_f32_e32 v35, v35
	s_nop 0
	v_mul_f32_e32 v61, 0x45800000, v35
	v_cndmask_b32_e32 v72, v35, v61, vcc
	v_pk_mul_f32 v[28:29], v[28:29], v[72:73] op_sel_hi:[1,0]
	v_pk_mul_f32 v[30:31], v[30:31], v[72:73] op_sel_hi:[1,0]
	v_pk_mul_f32 v[26:27], v[26:27], v[72:73] op_sel_hi:[1,0]
	v_pk_mul_f32 v[24:25], v[24:25], v[72:73] op_sel_hi:[1,0]
	v_pk_mul_f32 v[22:23], v[22:23], v[72:73] op_sel_hi:[1,0]
	v_pk_mul_f32 v[20:21], v[20:21], v[72:73] op_sel_hi:[1,0]
	v_pk_mul_f32 v[18:19], v[18:19], v[72:73] op_sel_hi:[1,0]
	v_pk_mul_f32 v[16:17], v[16:17], v[72:73] op_sel_hi:[1,0]
	v_pk_mul_f32 v[14:15], v[14:15], v[72:73] op_sel_hi:[1,0]
	v_pk_mul_f32 v[12:13], v[12:13], v[72:73] op_sel_hi:[1,0]
	v_pk_mul_f32 v[10:11], v[10:11], v[72:73] op_sel_hi:[1,0]
	v_pk_mul_f32 v[8:9], v[8:9], v[72:73] op_sel_hi:[1,0]
	v_pk_mul_f32 v[6:7], v[6:7], v[72:73] op_sel_hi:[1,0]
	v_pk_mul_f32 v[4:5], v[4:5], v[72:73] op_sel_hi:[1,0]
	v_pk_mul_f32 v[2:3], v[2:3], v[72:73] op_sel_hi:[1,0]
	v_pk_mul_f32 v[0:1], v[0:1], v[72:73] op_sel_hi:[1,0]
	v_pk_fma_f32 v[30:31], v[66:67], v[30:31], v[70:71]
	v_pk_fma_f32 v[28:29], v[64:65], v[28:29], v[68:69]
	global_store_dwordx4 v[74:75], v[28:31], off
	v_mov_b64_e32 v[62:63], v[92:93]
	v_mov_b64_e32 v[64:65], v[94:95]
	v_mov_b64_e32 v[66:67], v[124:125]
	v_mov_b64_e32 v[68:69], v[126:127]
	v_add_co_u32_e32 v70, vcc, s69, v74
	v_pk_fma_f32 v[24:25], v[62:63], v[24:25], v[66:67]
	v_pk_fma_f32 v[26:27], v[64:65], v[26:27], v[68:69]
	global_store_dwordx4 v[74:75], v[24:27], off offset:1024
	v_mov_b64_e32 v[62:63], v[96:97]
	v_mov_b64_e32 v[64:65], v[98:99]
	v_mov_b64_e32 v[66:67], v[128:129]
	v_mov_b64_e32 v[68:69], v[130:131]
	v_addc_co_u32_e32 v71, vcc, 0, v75, vcc
	v_pk_fma_f32 v[20:21], v[62:63], v[20:21], v[66:67]
	v_pk_fma_f32 v[22:23], v[64:65], v[22:23], v[68:69]
	global_store_dwordx4 v[74:75], v[20:23], off offset:2048
	v_mov_b64_e32 v[62:63], v[100:101]
	v_mov_b64_e32 v[64:65], v[102:103]
	v_mov_b64_e32 v[66:67], v[132:133]
	v_mov_b64_e32 v[68:69], v[134:135]
	v_pk_fma_f32 v[16:17], v[62:63], v[16:17], v[66:67]
	v_pk_fma_f32 v[18:19], v[64:65], v[18:19], v[68:69]
	global_store_dwordx4 v[74:75], v[16:19], off offset:3072
	v_mov_b64_e32 v[62:63], v[104:105]
	v_mov_b64_e32 v[64:65], v[106:107]
	v_mov_b64_e32 v[66:67], v[136:137]
	v_mov_b64_e32 v[68:69], v[138:139]
	v_pk_fma_f32 v[12:13], v[62:63], v[12:13], v[66:67]
	v_pk_fma_f32 v[14:15], v[64:65], v[14:15], v[68:69]
	global_store_dwordx4 v[70:71], v[12:15], off
	v_mov_b64_e32 v[62:63], v[108:109]
	v_mov_b64_e32 v[64:65], v[110:111]
	v_mov_b64_e32 v[66:67], v[140:141]
	v_mov_b64_e32 v[68:69], v[142:143]
	v_pk_fma_f32 v[8:9], v[62:63], v[8:9], v[66:67]
	v_pk_fma_f32 v[10:11], v[64:65], v[10:11], v[68:69]
	global_store_dwordx4 v[70:71], v[8:11], off offset:1024
	v_mov_b64_e32 v[62:63], v[112:113]
	v_mov_b64_e32 v[64:65], v[114:115]
	v_mov_b64_e32 v[66:67], v[144:145]
	v_mov_b64_e32 v[68:69], v[146:147]
	v_pk_fma_f32 v[4:5], v[62:63], v[4:5], v[66:67]
	v_pk_fma_f32 v[6:7], v[64:65], v[6:7], v[68:69]
	global_store_dwordx4 v[70:71], v[4:7], off offset:2048
	v_mov_b64_e32 v[62:63], v[116:117]
	v_mov_b64_e32 v[64:65], v[118:119]
	v_mov_b64_e32 v[66:67], v[150:151]
	v_mov_b64_e32 v[68:69], v[152:153]
	v_pk_fma_f32 v[0:1], v[62:63], v[0:1], v[66:67]
	v_pk_fma_f32 v[2:3], v[64:65], v[2:3], v[68:69]
	global_store_dwordx4 v[70:71], v[0:3], off offset:3072
	s_andn2_b64 vcc, exec, s[22:23]
	s_cbranch_vccnz .LBB0_344
	s_branch .Lln_skipdrain

; __device__ __forceinline__ void row_stats(const f32x4 (&v)[8], float& mean, float& rstd) {
;     float s = 0.f;
; #pragma unroll
;     for (int i = 0; i < 8; ++i) s += v[i][0] + v[i][1] + v[i][2] + v[i][3];
;     mean = wsum(s) * (1.f / 2048.f);
;     float q = 0.f;
; #pragma unroll
;     for (int i = 0; i < 8; ++i) { const f32x4 d = v[i] - mean; q += d[0] * d[0] + d[1] * d[1] + d[2] * d[2] + d[3] * d[3]; }
;     rstd = rsqrtf(wsum(q) * (1.f / 2048.f) + LN_EPS);
; __device__ void phase_ln(const Params& p, int l) {
;     ...
;         row_stats(v, mean, rstd);
;         const float* md = p.MOD + (size_t)(l * 3 + (isctx ? 2 : b)) * 6144;
;         u16* ur = p.U + (size_t)row * 2048;
; #pragma unroll
;         for (int i = 0; i < 8; ++i) { const f32x4 sh = *(const f32x4*)(md + i * 256 + lane * 4), sc = *(const f32x4*)(md + 2048 + i * 256 + lane * 4);
.Lln_skipdrain:
	v_add_f32_e32 v35, v28, v29
	v_add_f32_e32 v35, v30, v35
	v_add_f32_e32 v61, v24, v25
	v_add_f32_e32 v35, v31, v35
	v_add_f32_e32 v61, v26, v61
	v_add_f32_e32 v35, 0, v35
	v_add_f32_e32 v61, v27, v61
	v_add_f32_e32 v35, v61, v35
	v_add_f32_e32 v61, v20, v21
	v_add_f32_e32 v61, v22, v61
	v_add_f32_e32 v61, v23, v61
	v_add_f32_e32 v35, v61, v35
	v_add_f32_e32 v61, v16, v17
	v_mov_b32_e32 v62, v8
	v_mov_b32_e32 v63, v12
	v_mov_b32_e32 v64, v9
	v_mov_b32_e32 v65, v13
	v_add_f32_e32 v61, v18, v61
	v_pk_add_f32 v[62:63], v[62:63], v[64:65]
	v_mov_b32_e32 v64, v10
	v_mov_b32_e32 v65, v14
	v_add_f32_e32 v61, v19, v61
	v_pk_add_f32 v[62:63], v[64:65], v[62:63]
	v_mov_b32_e32 v64, v11
	v_mov_b32_e32 v65, v15
	v_add_f32_e32 v35, v61, v35
	v_pk_add_f32 v[62:63], v[64:65], v[62:63]
	v_mov_b32_e32 v64, v1
	v_add_f32_e32 v35, v63, v35
	v_add_f32_e32 v35, v62, v35
	v_mov_b32_e32 v62, v0
	v_mov_b32_e32 v63, v4
	v_mov_b32_e32 v65, v5
	v_pk_add_f32 v[62:63], v[62:63], v[64:65]
	v_mov_b32_e32 v64, v2
	v_mov_b32_e32 v65, v6
	v_pk_add_f32 v[62:63], v[64:65], v[62:63]
	v_mov_b32_e32 v64, v3
	v_mov_b32_e32 v65, v7
	v_pk_add_f32 v[62:63], v[64:65], v[62:63]
	v_cmp_lt_i32_e32 vcc, v211, v210
	v_add_f32_e32 v35, v63, v35
	v_add_f32_e32 v35, v62, v35
	v_cndmask_b32_e32 v61, v208, v211, vcc
	v_lshlrev_b32_e32 v82, 2, v61
	ds_bpermute_b32 v61, v82, v35
	v_cmp_lt_i32_e32 vcc, v212, v210
	v_lshrrev_b32_e32 v60, 13, v60
	v_cndmask_b32_e64 v60, v60, 2, s[6:7]
	s_waitcnt lgkmcnt(0)
	v_add_f32_e32 v35, v35, v61
	v_cndmask_b32_e32 v61, v208, v212, vcc
	v_lshlrev_b32_e32 v83, 2, v61
	ds_bpermute_b32 v61, v83, v35
	v_cmp_lt_i32_e32 vcc, v213, v210
	s_waitcnt lgkmcnt(0)
	v_add_f32_e32 v35, v35, v61
	v_cndmask_b32_e32 v61, v208, v213, vcc
	v_lshlrev_b32_e32 v84, 2, v61
	ds_bpermute_b32 v61, v84, v35
	v_cmp_lt_i32_e32 vcc, v214, v210
	s_waitcnt lgkmcnt(0)
	v_add_f32_e32 v35, v35, v61
	v_cndmask_b32_e32 v61, v208, v214, vcc
	v_lshlrev_b32_e32 v85, 2, v61
	ds_bpermute_b32 v61, v85, v35
	v_cmp_lt_i32_e32 vcc, v215, v210
	s_waitcnt lgkmcnt(0)
	v_add_f32_e32 v35, v35, v61
	v_cndmask_b32_e32 v61, v208, v215, vcc
	v_lshlrev_b32_e32 v86, 2, v61
	ds_bpermute_b32 v61, v86, v35
	v_cmp_lt_i32_e32 vcc, v216, v210
	s_waitcnt lgkmcnt(0)
	v_add_f32_e32 v35, v35, v61
	v_cndmask_b32_e32 v61, v208, v216, vcc
	v_lshlrev_b32_e32 v87, 2, v61
	ds_bpermute_b32 v61, v87, v35
	s_waitcnt lgkmcnt(0)
	v_add_f32_e32 v35, v35, v61
	v_fmac_f32_e32 v29, 0xba000000, v35
	v_fmac_f32_e32 v25, 0xba000000, v35
	v_fmamk_f32 v28, v35, 0xba000000, v28
	v_mul_f32_e32 v61, v29, v29
	v_fmamk_f32 v68, v35, 0xba000000, v26
	v_fmamk_f32 v24, v35, 0xba000000, v24
	v_mul_f32_e32 v26, v25, v25
	v_fmac_f32_e32 v21, 0xba000000, v35
	v_fmamk_f32 v30, v35, 0xba000000, v30
	v_fmac_f32_e32 v61, v28, v28
	v_fmac_f32_e32 v26, v24, v24
	v_fmamk_f32 v70, v35, 0xba000000, v22
	v_fmamk_f32 v20, v35, 0xba000000, v20
	v_mul_f32_e32 v22, v21, v21
	v_fmac_f32_e32 v17, 0xba000000, v35
	v_fmamk_f32 v31, v35, 0xba000000, v31
	v_fmac_f32_e32 v61, v30, v30
	v_fmamk_f32 v69, v35, 0xba000000, v27
	v_fmac_f32_e32 v26, v68, v68
	v_fmac_f32_e32 v22, v20, v20
	v_fmamk_f32 v72, v35, 0xba000000, v18
	v_fmamk_f32 v16, v35, 0xba000000, v16
	v_mul_f32_e32 v18, v17, v17
	v_fmac_f32_e32 v61, v31, v31
	v_fmac_f32_e32 v26, v69, v69
	v_fmamk_f32 v71, v35, 0xba000000, v23
	v_fmac_f32_e32 v22, v70, v70
	v_fmac_f32_e32 v18, v16, v16
	v_add_f32_e32 v26, v61, v26
	v_fmac_f32_e32 v22, v71, v71
	v_fmamk_f32 v73, v35, 0xba000000, v19
	v_fmac_f32_e32 v18, v72, v72
	v_add_f32_e32 v22, v22, v26
	v_fmac_f32_e32 v18, v73, v73
	v_fmamk_f32 v13, v35, 0xba000000, v13
	v_fmamk_f32 v9, v35, 0xba000000, v9
	v_add_f32_e32 v26, v18, v22
	v_fmac_f32_e32 v12, 0xba000000, v35
	v_fmac_f32_e32 v8, 0xba000000, v35
	v_mov_b32_e32 v22, v9
	v_mov_b32_e32 v23, v13
	v_mov_b32_e32 v18, v8
	v_mov_b32_e32 v19, v12
	v_pk_mul_f32 v[22:23], v[22:23], v[22:23]
	v_add_u32_e32 v27, s44, v60
	v_pk_fma_f32 v[18:19], v[18:19], v[18:19], v[22:23]
	v_mov_b64_e32 v[22:23], s[16:17]
	v_mad_i64_i32 v[22:23], s[6:7], v27, s65, v[22:23]
	v_lshl_add_u64 v[74:75], v[22:23], 0, v[148:149]
	s_movk_i32 s6, 0x3000
	v_add_co_u32_e32 v76, vcc, s6, v74
	v_fmamk_f32 v14, v35, 0xba000000, v14
	s_nop 0
	v_addc_co_u32_e32 v77, vcc, 0, v75, vcc
	global_load_dwordx4 v[60:63], v[74:75], off
	global_load_dwordx4 v[64:67], v[76:77], off offset:-4096
	v_fmamk_f32 v10, v35, 0xba000000, v10
	v_fmamk_f32 v5, v35, 0xba000000, v5
	v_fmamk_f32 v1, v35, 0xba000000, v1
	v_fmamk_f32 v15, v35, 0xba000000, v15
	v_fmamk_f32 v11, v35, 0xba000000, v11
	v_mov_b32_e32 v22, v10
	v_mov_b32_e32 v23, v14
	v_fmamk_f32 v79, v35, 0xba000000, v7
	v_fmamk_f32 v78, v35, 0xba000000, v6
	v_fmac_f32_e32 v4, 0xba000000, v35
	v_fmac_f32_e32 v0, 0xba000000, v35
	v_mov_b32_e32 v6, v1
	v_mov_b32_e32 v7, v5
	v_pk_fma_f32 v[18:19], v[22:23], v[22:23], v[18:19]
	v_mov_b32_e32 v22, v11
	v_mov_b32_e32 v23, v15
	v_fmamk_f32 v81, v35, 0xba000000, v3
	v_fmamk_f32 v80, v35, 0xba000000, v2
	v_mov_b32_e32 v2, v0
	v_mov_b32_e32 v3, v4
	v_pk_mul_f32 v[6:7], v[6:7], v[6:7]
	v_pk_fma_f32 v[18:19], v[22:23], v[22:23], v[18:19]
	v_pk_fma_f32 v[2:3], v[2:3], v[2:3], v[6:7]
	v_mov_b32_e32 v6, v80
	v_mov_b32_e32 v7, v78
	v_add_f32_e32 v19, v19, v26
	v_pk_fma_f32 v[2:3], v[6:7], v[6:7], v[2:3]
	v_mov_b32_e32 v6, v81
	v_mov_b32_e32 v7, v79
	v_add_f32_e32 v18, v18, v19
	v_pk_fma_f32 v[2:3], v[6:7], v[6:7], v[2:3]
	s_mov_b64 s[6:7], 0x2000
	v_add_f32_e32 v3, v3, v18
	v_add_f32_e32 v2, v2, v3
	ds_bpermute_b32 v3, v82, v2
	s_waitcnt lgkmcnt(0)
	v_add_f32_e32 v2, v2, v3
	ds_bpermute_b32 v3, v83, v2
	s_waitcnt lgkmcnt(0)
	v_add_f32_e32 v2, v2, v3
	ds_bpermute_b32 v3, v84, v2
	s_waitcnt lgkmcnt(0)
; __device__ __forceinline__ unsigned pk2(float lo, float hi) { const f32x2_t v = {lo, hi}; return __builtin_bit_cast(unsigned, __builtin_convertvector(v, bf16x2_t)); }
; __device__ void phase_ln(const Params& p, int l) {
;     ...
;         row_stats(v, mean, rstd);
;         const float* md = p.MOD + (size_t)(l * 3 + (isctx ? 2 : b)) * 6144;
;         u16* ur = p.U + (size_t)row * 2048;
; #pragma unroll
;         for (int i = 0; i < 8; ++i) { const f32x4 sh = *(const f32x4*)(md + i * 256 + lane * 4), sc = *(const f32x4*)(md + 2048 + i * 256 + lane * 4);
;             const f32x4 o = (v[i] - mean) * rstd * (sc + 1.f) + sh;
;             u32x2 w; w.x = pk2(o[0], o[1]); w.y = pk2(o[2], o[3]);
;             *(u32x2*)(ur + i * 256 + lane * 4) = w; }
	v_add_f32_e32 v2, v2, v3
	ds_bpermute_b32 v3, v85, v2
	s_waitcnt lgkmcnt(0)
	v_add_f32_e32 v2, v2, v3
	ds_bpermute_b32 v3, v86, v2
	s_waitcnt lgkmcnt(0)
	v_add_f32_e32 v2, v2, v3
	ds_bpermute_b32 v3, v87, v2
	s_waitcnt lgkmcnt(0)
	v_add_f32_e32 v2, v2, v3
	v_fmamk_f32 v2, v2, 0x3a000000, v207
	v_mul_f32_e32 v3, 0x4b800000, v2
	v_cmp_gt_f32_e32 vcc, s41, v2
	s_waitcnt vmcnt(0)
	v_pk_add_f32 v[22:23], v[66:67], 1.0 op_sel_hi:[1,0]
	v_cndmask_b32_e32 v2, v2, v3, vcc
	v_rsq_f32_e32 v2, v2
	v_pk_add_f32 v[26:27], v[64:65], 1.0 op_sel_hi:[1,0]
	v_mul_f32_e32 v3, 0x45800000, v2
	v_cndmask_b32_e32 v82, v2, v3, vcc
	v_pk_mul_f32 v[6:7], v[28:29], v[82:83] op_sel_hi:[1,0]
	v_pk_mul_f32 v[18:19], v[30:31], v[82:83] op_sel_hi:[1,0]
	v_pk_fma_f32 v[6:7], v[26:27], v[6:7], v[60:61]
	v_pk_fma_f32 v[18:19], v[22:23], v[18:19], v[62:63]
	v_cvt_pk_bf16_f32 v6, v6, v7
	v_cvt_pk_bf16_f32 v7, v18, v19
	v_lshl_add_u64 v[2:3], v[74:75], 0, s[6:7]
	global_store_dwordx2 v[56:57], v[6:7], off
	v_add_co_u32_e32 v232, vcc, s69, v74
	global_load_dwordx4 v[158:161], v[2:3], off offset:1024
	global_load_dwordx4 v[162:165], v[74:75], off offset:1024
	v_addc_co_u32_e32 v233, vcc, 0, v75, vcc
	global_load_dwordx4 v[166:169], v[2:3], off offset:2048
	global_load_dwordx4 v[170:173], v[74:75], off offset:2048
	global_load_dwordx4 v[174:177], v[2:3], off offset:3072
	global_load_dwordx4 v[178:181], v[74:75], off offset:3072
	global_load_dwordx4 v[182:185], v[76:77], off
	global_load_dwordx4 v[186:189], v[232:233], off
	global_load_dwordx4 v[190:193], v[76:77], off offset:1024
	global_load_dwordx4 v[194:197], v[232:233], off offset:1024
	global_load_dwordx4 v[198:201], v[76:77], off offset:2048
	global_load_dwordx4 v[202:205], v[232:233], off offset:2048
	global_load_dwordx4 v[224:227], v[76:77], off offset:3072
	global_load_dwordx4 v[228:231], v[232:233], off offset:3072
	v_pk_mul_f32 v[6:7], v[24:25], v[82:83] op_sel_hi:[1,0]
	v_pk_mul_f32 v[18:19], v[68:69], v[82:83] op_sel_hi:[1,0]
	v_pk_mul_f32 v[0:1], v[0:1], v[82:83] op_sel_hi:[1,0]
	s_waitcnt vmcnt(0)
	v_mov_b64_e32 v[26:27], v[158:159]
	v_mov_b64_e32 v[28:29], v[160:161]
	v_mov_b64_e32 v[60:61], v[162:163]
	v_mov_b64_e32 v[62:63], v[164:165]
	v_pk_add_f32 v[22:23], v[28:29], 1.0 op_sel_hi:[1,0]
	v_pk_add_f32 v[24:25], v[26:27], 1.0 op_sel_hi:[1,0]
	v_pk_fma_f32 v[18:19], v[22:23], v[18:19], v[62:63]
	v_pk_fma_f32 v[6:7], v[24:25], v[6:7], v[60:61]
	s_nop 0
	v_cvt_pk_bf16_f32 v6, v6, v7
	v_cvt_pk_bf16_f32 v7, v18, v19
	global_store_dwordx2 v[56:57], v[6:7], off offset:512
	v_pk_mul_f32 v[6:7], v[20:21], v[82:83] op_sel_hi:[1,0]
	v_pk_mul_f32 v[18:19], v[70:71], v[82:83] op_sel_hi:[1,0]
	v_mov_b64_e32 v[22:23], v[166:167]
	v_mov_b64_e32 v[24:25], v[168:169]
	v_mov_b64_e32 v[26:27], v[170:171]
	v_mov_b64_e32 v[28:29], v[172:173]
	v_pk_add_f32 v[20:21], v[24:25], 1.0 op_sel_hi:[1,0]
	v_pk_add_f32 v[22:23], v[22:23], 1.0 op_sel_hi:[1,0]
	v_pk_fma_f32 v[18:19], v[20:21], v[18:19], v[28:29]
	v_pk_fma_f32 v[6:7], v[22:23], v[6:7], v[26:27]
	s_nop 0
	v_cvt_pk_bf16_f32 v6, v6, v7
	v_cvt_pk_bf16_f32 v7, v18, v19
	global_store_dwordx2 v[56:57], v[6:7], off offset:1024
	v_pk_mul_f32 v[2:3], v[16:17], v[82:83] op_sel_hi:[1,0]
	v_pk_mul_f32 v[6:7], v[72:73], v[82:83] op_sel_hi:[1,0]
	v_mov_b64_e32 v[18:19], v[174:175]
	v_mov_b64_e32 v[20:21], v[176:177]
	v_mov_b64_e32 v[22:23], v[178:179]
	v_mov_b64_e32 v[24:25], v[180:181]
	v_pk_add_f32 v[16:17], v[20:21], 1.0 op_sel_hi:[1,0]
	v_pk_add_f32 v[18:19], v[18:19], 1.0 op_sel_hi:[1,0]
	v_pk_fma_f32 v[6:7], v[16:17], v[6:7], v[24:25]
	v_pk_fma_f32 v[2:3], v[18:19], v[2:3], v[22:23]
	v_add_co_u32_e32 v24, vcc, s69, v74
	v_cvt_pk_bf16_f32 v2, v2, v3
	v_cvt_pk_bf16_f32 v3, v6, v7
	global_store_dwordx2 v[56:57], v[2:3], off offset:1536
	v_addc_co_u32_e32 v25, vcc, 0, v75, vcc
	v_pk_mul_f32 v[2:3], v[12:13], v[82:83] op_sel_hi:[1,0]
	v_pk_mul_f32 v[6:7], v[14:15], v[82:83] op_sel_hi:[1,0]
	v_mov_b64_e32 v[16:17], v[182:183]
	v_mov_b64_e32 v[18:19], v[184:185]
	v_mov_b64_e32 v[20:21], v[186:187]
	v_mov_b64_e32 v[22:23], v[188:189]
	v_pk_add_f32 v[12:13], v[18:19], 1.0 op_sel_hi:[1,0]
	v_pk_add_f32 v[14:15], v[16:17], 1.0 op_sel_hi:[1,0]
	v_pk_fma_f32 v[6:7], v[12:13], v[6:7], v[22:23]
	v_pk_fma_f32 v[2:3], v[14:15], v[2:3], v[20:21]
	s_nop 0
	v_cvt_pk_bf16_f32 v2, v2, v3
	v_cvt_pk_bf16_f32 v3, v6, v7
	global_store_dwordx2 v[56:57], v[2:3], off offset:2048
	v_pk_mul_f32 v[2:3], v[8:9], v[82:83] op_sel_hi:[1,0]
	v_pk_mul_f32 v[6:7], v[10:11], v[82:83] op_sel_hi:[1,0]
	v_mov_b64_e32 v[12:13], v[190:191]
	v_mov_b64_e32 v[14:15], v[192:193]
	v_mov_b64_e32 v[16:17], v[194:195]
	v_mov_b64_e32 v[18:19], v[196:197]
	v_pk_add_f32 v[8:9], v[14:15], 1.0 op_sel_hi:[1,0]
	v_pk_add_f32 v[10:11], v[12:13], 1.0 op_sel_hi:[1,0]
	v_pk_fma_f32 v[6:7], v[8:9], v[6:7], v[18:19]
	v_pk_fma_f32 v[2:3], v[10:11], v[2:3], v[16:17]
	s_nop 0
	v_cvt_pk_bf16_f32 v2, v2, v3
	v_cvt_pk_bf16_f32 v3, v6, v7
	global_store_dwordx2 v[56:57], v[2:3], off offset:2560
	v_pk_mul_f32 v[2:3], v[4:5], v[82:83] op_sel_hi:[1,0]
	v_pk_mul_f32 v[4:5], v[78:79], v[82:83] op_sel_hi:[1,0]
	v_mov_b64_e32 v[6:7], v[198:199]
	v_mov_b64_e32 v[8:9], v[200:201]
	v_mov_b64_e32 v[10:11], v[202:203]
	v_mov_b64_e32 v[12:13], v[204:205]
	v_pk_add_f32 v[8:9], v[8:9], 1.0 op_sel_hi:[1,0]
	v_pk_add_f32 v[6:7], v[6:7], 1.0 op_sel_hi:[1,0]
	v_pk_fma_f32 v[4:5], v[8:9], v[4:5], v[12:13]
	v_pk_fma_f32 v[2:3], v[6:7], v[2:3], v[10:11]
	v_pk_mul_f32 v[10:11], v[80:81], v[82:83] op_sel_hi:[1,0]
	v_cvt_pk_bf16_f32 v2, v2, v3
	v_cvt_pk_bf16_f32 v3, v4, v5
	global_store_dwordx2 v[56:57], v[2:3], off offset:3072
	v_mov_b64_e32 v[2:3], v[224:225]
	v_mov_b64_e32 v[4:5], v[226:227]
	v_mov_b64_e32 v[6:7], v[228:229]
	v_mov_b64_e32 v[8:9], v[230:231]
	v_pk_add_f32 v[4:5], v[4:5], 1.0 op_sel_hi:[1,0]
	v_pk_add_f32 v[2:3], v[2:3], 1.0 op_sel_hi:[1,0]
	v_pk_fma_f32 v[4:5], v[4:5], v[10:11], v[8:9]
	v_pk_fma_f32 v[0:1], v[2:3], v[0:1], v[6:7]
	s_nop 0
	v_cvt_pk_bf16_f32 v0, v0, v1
	v_cvt_pk_bf16_f32 v1, v4, v5
	global_store_dwordx2 v[56:57], v[0:1], off offset:3584
	s_branch .LBB0_344
